# k=2 rebalance: chunk workgroups take rows [0,2048) of the two row passes after their gMLP chunk, the other workgroups rows [2048,18432)
# speedup vs baseline: 1.0077x; 1.0060x over previous
; __device__ __forceinline__ float quad_sum(float x) { x = DPP_ADD(x, 0xB1); x = DPP_ADD(x, 0x4E); return x; }
; __device__ __forceinline__ float quad_xor2(float x) { return __builtin_bit_cast(float, __builtin_amdgcn_update_dpp(0, __builtin_bit_cast(int, x), 0x4E, 0xf, 0xf, true)); }
; __device__ __forceinline__ void qk_rows(CArgs& a, int l, int gw, int ngw, int lane) {
;     bf16_t* Q = (bf16_t*)(a.ws + WS_Q); bf16_t* K = (bf16_t*)(a.ws + WS_K);
;     const float* RC = (const float*)(a.ws + WS_ROPE); const float* RS = RC + 2048 * 32;
;     const int part = lane & 3;
;     float gq[16], gk[16];
;     load16f(a.in[12] + l * 64 + 16 * part, gq); load16f(a.in[13] + l * 64 + 16 * part, gk);
;     for (int row = gw; row < M; row += ngw) {
;         float xq[16], xk[16], cs[16], sn[16];
;         unpack16(Q + (size_t)row * 1024 + 16 * lane, xq); unpack16(K + (size_t)row * 1024 + 16 * lane, xk);
;         const bool lat = row < ML;
;         if (lat) { const int t = row & 2047; load16f(RC + t * 32 + 16 * (part & 1), cs); load16f(RS + t * 32 + 16 * (part & 1), sn); }
;         float sq = 0.f, sk = 0.f;
; #pragma unroll
;         for (int j = 0; j < 16; ++j) { sq += xq[j] * xq[j]; sk += xk[j] * xk[j]; }
;         const float rq = rsqrtf(quad_sum(sq) * (1.f / 64.f) + 1e-6f), rk = rsqrtf(quad_sum(sk) * (1.f / 64.f) + 1e-6f);
; #pragma unroll
;         for (int j = 0; j < 16; ++j) { xq[j] = xq[j] * rq * gq[j]; xk[j] = xk[j] * rk * gk[j]; }
;         if (lat) {
;             const float sgn = part < 2 ? -1.f : 1.f;
; #pragma unroll
;             for (int j = 0; j < 16; ++j) {
;                 const float pq = quad_xor2(xq[j]), pk = quad_xor2(xk[j]);
;                 xq[j] = xq[j] * cs[j] + sgn * pq * sn[j]; xk[j] = xk[j] * cs[j] + sgn * pk * sn[j];
;             }
;         }
; #pragma unroll
;         for (int j = 0; j < 16; ++j) xq[j] *= QSCALE;
;         pack16(Q + (size_t)row * 1024 + 16 * lane, xq); pack16(K + (size_t)row * 1024 + 16 * lane, xk);
; __global__ void __launch_bounds__(512, 2) mega_fwd(Args a_) {
;     ...
;             case 2: if constexpr (PH_ON(2)) {
;                 for (int u = ti.bid; u < Mr / 128; u += ti.nblk) gmlp_unit(ti, a, l, u, lds);
;                 qk_rows(a, l, gw, ngw, lane);
;                 lora_in_rows(a, l, gw, ngw, lane);
.LBB0_449:
	s_movk_i32 s99, 0x4800
	s_sub_i32 s3, s0, s10
	s_cmp_lt_i32 s3, 64
	s_cbranch_scc1 .Lrows_default
	s_cmp_lt_i32 s2, s10
	s_cbranch_scc1 .Lrows_none
	s_sub_i32 s2, s2, s10
	s_mov_b32 s0, s3
	v_readlane_b32 s3, v255, 42
	s_lshl_b32 s48, s2, 3
	s_lshl_b32 s80, s0, 3
	s_nop 1
	s_add_i32 s48, s48, s3
	s_addk_i32 s48, 0x800
	s_branch .Lrows_default
.Lrows_none:
	s_mov_b32 s0, s10
	v_readlane_b32 s3, v255, 42
	s_lshl_b32 s48, s2, 3
	s_lshl_b32 s80, s0, 3
	s_nop 1
	s_add_i32 s48, s48, s3
	s_movk_i32 s99, 0x800
.Lrows_default:
	s_cmp_lt_i32 s48, s99
	s_cselect_b64 s[42:43], -1, 0
	s_cmp_ge_i32 s48, s99
	v_lshlrev_b32_e32 v82, 5, v180
	s_cbranch_scc1 .LBB0_457
	s_load_dwordx4 s[4:7], s[74:75], 0x60
	s_lshl_b32 s10, s62, 6
	s_ashr_i32 s11, s10, 31
	s_lshl_b64 s[10:11], s[10:11], 2
	v_and_b32_e32 v36, 3, v178
	s_waitcnt lgkmcnt(0)
	s_add_u32 s6, s6, s10
	s_addc_u32 s7, s7, s11
	s_add_u32 s4, s4, s10
	v_lshlrev_b32_e32 v0, 6, v36
	s_addc_u32 s5, s5, s11
	global_load_dwordx4 v[2:5], v0, s[6:7] offset:48
	global_load_dwordx4 v[6:9], v0, s[6:7] offset:32
	global_load_dwordx4 v[10:13], v0, s[6:7] offset:16
	global_load_dwordx4 v[14:17], v0, s[6:7]
	global_load_dwordx4 v[18:21], v0, s[4:5] offset:48
	global_load_dwordx4 v[22:25], v0, s[4:5] offset:32
	global_load_dwordx4 v[26:29], v0, s[4:5] offset:16
	global_load_dwordx4 v[30:33], v0, s[4:5]
	s_load_dwordx2 s[6:7], s[74:75], 0x110
	v_lshlrev_b32_e32 v0, 6, v180
	v_and_b32_e32 v0, 64, v0
	s_mov_b64 s[4:5], 0x2c200000
	v_readlane_b32 s3, v255, 42
	s_waitcnt lgkmcnt(0)
	v_lshl_add_u64 v[34:35], s[6:7], 0, v[0:1]
	v_lshl_add_u64 v[84:85], v[34:35], 0, s[4:5]
	s_mov_b64 s[4:5], 0x2c240000
	s_lshl_b32 s1, s2, 8
	s_lshl_b32 s3, s3, 5
	s_ashr_i32 s49, s48, 31
	v_lshl_add_u64 v[86:87], v[34:35], 0, s[4:5]
	s_add_i32 s1, s1, s3
	s_lshl_b32 s1, s48, 5
	s_lshl_b32 s3, s0, 8
	s_lshl_b64 s[4:5], s[48:49], 11
	s_add_u32 s4, s6, s4
	v_cmp_gt_u32_e32 vcc, 2, v36
	v_mov_b32_e32 v83, v1
	s_addc_u32 s5, s7, s5
	v_cndmask_b32_e64 v88, 1.0, -1.0, vcc
	v_lshl_add_u64 v[34:35], s[4:5], 0, v[82:83]
	s_mov_b64 s[4:5], 0xca00010
	s_ashr_i32 s81, s80, 31
	v_mov_b32_e32 v89, v88
	v_lshl_add_u64 v[90:91], v[34:35], 0, s[4:5]
	s_lshl_b64 s[44:45], s[80:81], 11
	s_mov_b32 s6, s48
	s_branch .LBB0_452
.LBB0_451:
	s_mov_b32 s4, 0x3e38aa3b
	v_pk_mul_f32 v[96:97], v[100:101], s[4:5] op_sel_hi:[1,0]
	v_pk_mul_f32 v[102:103], v[102:103], s[4:5] op_sel_hi:[1,0]
	v_pk_mul_f32 v[114:115], v[104:105], s[4:5] op_sel_hi:[1,0]
	v_pk_mul_f32 v[104:105], v[106:107], s[4:5] op_sel_hi:[1,0]
	v_pk_mul_f32 v[106:107], v[108:109], s[4:5] op_sel_hi:[1,0]
	v_pk_mul_f32 v[108:109], v[110:111], s[4:5] op_sel_hi:[1,0]
	v_pk_mul_f32 v[110:111], v[112:113], s[4:5] op_sel_hi:[1,0]
	v_pk_mul_f32 v[80:81], v[80:81], s[4:5] op_sel_hi:[1,0]
	s_mov_b32 s4, 0xfdc00000
	v_cvt_pk_bf16_f32 v100, v80, v81
	v_add_co_u32_e32 v80, vcc, s4, v90
	v_cvt_pk_bf16_f32 v104, v104, v105
	v_cvt_pk_bf16_f32 v101, v96, v97
	v_cvt_pk_bf16_f32 v105, v106, v107
	v_cvt_pk_bf16_f32 v102, v102, v103
	v_cvt_pk_bf16_f32 v106, v108, v109
	v_cvt_pk_bf16_f32 v103, v114, v115
	v_cvt_pk_bf16_f32 v107, v110, v111
	v_addc_co_u32_e32 v81, vcc, -1, v91, vcc
	v_cvt_pk_bf16_f32 v66, v66, v67
	v_cvt_pk_bf16_f32 v67, v68, v69
	v_cvt_pk_bf16_f32 v68, v70, v71
	v_cvt_pk_bf16_f32 v69, v72, v73
	s_add_i32 s6, s6, s80
	s_add_i32 s1, s1, s3
	global_store_dwordx4 v[94:95], v[100:103], off
	global_store_dwordx4 v[80:81], v[104:107], off
	v_cvt_pk_bf16_f32 v74, v74, v75
	v_cvt_pk_bf16_f32 v75, v76, v77
	v_cvt_pk_bf16_f32 v76, v78, v79
	v_cvt_pk_bf16_f32 v77, v98, v99
	global_store_dwordx4 v[90:91], v[66:69], off offset:-16
	global_store_dwordx4 v[90:91], v[74:77], off
	s_cmp_lt_i32 s6, s99
	v_lshl_add_u64 v[90:91], v[90:91], 0, s[44:45]
	s_cbranch_scc0 .LBB0_457

; __device__ __forceinline__ u32x4 pack8(f32x4 v0, f32x4 v1) { u32x4 o; o.x = pkbf(v0.x, v0.y); o.y = pkbf(v0.z, v0.w); o.z = pkbf(v1.x, v1.y); o.w = pkbf(v1.z, v1.w); return o; }
; __device__ __forceinline__ f32x4 sig4(f32x4 v) { return (f32x4){sigmoidf_(v.x), sigmoidf_(v.y), sigmoidf_(v.z), sigmoidf_(v.w)}; }
; __device__ __forceinline__ void lora_in_rows(CArgs& a, int l, int gw, int ngw, int lane) {
;     ...
;     for (int row = gw; row < M; row += ngw) {
;         int t, Tn; if (row < ML) { t = row & 2047; Tn = 2048; } else { t = (row - ML) & 255; Tn = 256; }
;         const bool hp = t > 0, hn = t < Tn - 1;
;         if (lane < 52) {
;             const bf16_t* p = RW + (size_t)row * RWP + 3072 + 8 * lane;
;             f32x4 x0, x1, p0 = {0.f, 0.f, 0.f, 0.f}, p1 = p0, n0 = p0, n1 = p0;
;             unpack8(*(const u32x4*)p, x0, x1);
;             if (hp) unpack8(*(const u32x4*)(p - RWP), p0, p1);
;             if (hn) unpack8(*(const u32x4*)(p + RWP), n0, n1);
;             f32x4 z0 = x0 + m0 * (0.5f * (p0 + n0) - x0), z1 = x1 + m1 * (0.5f * (p1 + n1) - x1);
;             const int j = 8 * lane;
;             if (j < 128) { z0 = (f32x4){tanhf(z0.x), tanhf(z0.y), tanhf(z0.z), tanhf(z0.w)}; z1 = (f32x4){tanhf(z1.x), tanhf(z1.y), tanhf(z1.z), tanhf(z1.w)}; *(u32x4*)(LW + (size_t)row * 128 + j) = pack8(z0, z1); }
;             else if (j < 256) { *(u32x4*)(LA + (size_t)row * 128 + j - 128) = pack8(z0, z1); }
;             else { *(u32x4*)(LG + (size_t)row * 256 + j - 256) = pack8(sig4(z0), sig4(z1)); }
;         } else {
;             unsigned z_ = 0u; asm volatile("" : "+v"(z_)); *(u32x4*)(LG + (size_t)row * 256 + 160 + (lane - 52) * 8) = (u32x4){z_, z_, z_, z_};
;         }
;     }
.LBB0_463:
	s_or_b64 exec, exec, s[56:57]
	s_add_i32 s1, s1, s80
	s_add_u32 s46, s46, s48
	s_addc_u32 s47, s47, s49
	s_add_u32 s50, s50, s52
	s_addc_u32 s51, s51, s53
	s_mul_i32 s3, s80, 0x1c00
	s_add_u32 s54, s54, s3
	s_mul_hi_i32 s3, s80, 0x1c00
	s_addc_u32 s55, s55, s3
	s_cmp_ge_i32 s1, s99
	s_cbranch_scc1 .LBB0_510
